# FFN-down phases walk their tiles in reverse order (t -> 511-t), so the most recently written SwiGLU rows are read first (memory-side cache reuse)
# baseline (speedup 1.0000x reference)
;     __host__ __device__ bool next(int i, Unit& u) const {
;         const long L = (long)i * G + c; if (L >= nwg) return false;
;         int wgid = (int)L; { const int q = nwg / NXCD, r = nwg % NXCD, xcd = wgid % NXCD, off = wgid / NXCD; wgid = (xcd < r ? xcd * (q + 1) : r * (q + 1) + (xcd - r) * q) + off; }
;         const int nig = WGM * nN, gid = wgid / nig, fm = gid * WGM, gsz = (nM - fm) < WGM ? (nM - fm) : WGM;
;         u.pm = fm + ((wgid % nig) % gsz); u.pn = (wgid % nig) / gsz; return true;
; template <class Epi, class Sched, bool ALIGN_EPI = false, bool SP2 = false>
; __device__ __forceinline__ void gemm_phase(PG8_LAS unsigned char* lds, const Gemm g, const Sched& S, const Epi& E) {
;     ...
;     if (!S.next(0, cur)) return;
.LBB0_250:
	s_or_b64 exec, exec, s[0:1]
	s_cmpk_lt_i32 s2, 0x200
	v_mov_b32_e32 v8, v204
	s_waitcnt lgkmcnt(0)
	s_barrier
	s_cselect_b64 s[0:1], -1, 0
	s_cmpk_gt_i32 s2, 0x1ff
	s_nop 0
	v_readfirstlane_b32 s3, v8
	s_cbranch_scc1 .LBB0_252
	s_sub_i32 s9, 0x1ff, s2
	s_lshr_b32 s6, s35, 29
	s_add_i32 s6, s9, s6
	s_and_b32 s7, s6, -8
	s_sub_i32 s7, s9, s7
	s_lshl_b32 s9, s7, 6
	s_ashr_i32 s6, s6, 3
	s_mul_i32 s8, s7, 0x41
	s_cmp_lt_i32 s7, 0
	s_cselect_b32 s7, s8, s9
	s_add_i32 s6, s7, s6
	s_ashr_i32 s7, s6, 31
	s_lshr_b32 s7, s7, 27
	s_add_i32 s7, s6, s7
	s_ashr_i32 s8, s7, 5
	s_andn2_b32 s7, s7, 31
	s_sub_i32 s6, s6, s7
	s_bfe_i32 s7, s6, 0x80000
	s_bfe_u32 s7, s7, 0x3000c
	s_add_i32 s7, s6, s7
	s_bfe_i32 s9, s7, 0x80000
	s_and_b32 s7, s7, 0xf8
	s_sub_i32 s6, s6, s7
	s_lshl_b32 s8, s8, 3
	s_sext_i32_i16 s9, s9
	s_sext_i32_i8 s6, s6
	s_add_i32 s90, s8, s6
	s_ashr_i32 s89, s9, 3

;     __host__ __device__ bool next(int i, Unit& u) const {
;         const long L = (long)i * G + c; if (L >= nwg) return false;
;         int wgid = (int)L; { const int q = nwg / NXCD, r = nwg % NXCD, xcd = wgid % NXCD, off = wgid / NXCD; wgid = (xcd < r ? xcd * (q + 1) : r * (q + 1) + (xcd - r) * q) + off; }
;         const int nig = WGM * nN, gid = wgid / nig, fm = gid * WGM, gsz = (nM - fm) < WGM ? (nM - fm) : WGM;
;         u.pm = fm + ((wgid % nig) % gsz); u.pn = (wgid % nig) / gsz; return true;
; template <class Epi, class Sched, bool ALIGN_EPI = false, bool SP2 = false>
; __device__ __forceinline__ void gemm_phase(PG8_LAS unsigned char* lds, const Gemm g, const Sched& S, const Epi& E) {
;     ...
;         const bool has_next = S.next(ui + 1, nxt);
.LBB0_258:
	s_add_i32 s62, s62, 1
	s_mul_i32 s0, s62, s19
	s_mul_hi_u32 s1, s62, s72
	s_add_i32 s1, s1, s0
	s_mul_i32 s0, s62, s72
	s_add_u32 s8, s0, s2
	s_addc_u32 s9, s1, s35
	v_cmp_gt_i64_e32 vcc, s[8:9], v[150:151]
	v_cmp_lt_i64_e64 s[0:1], s[8:9], v[148:149]
	s_cbranch_vccnz .LBB0_264
	s_sub_i32 s8, 0x1ff, s8
	s_ashr_i32 s3, s8, 31
	s_lshr_b32 s3, s3, 29
	s_add_i32 s3, s8, s3
	s_and_b32 s9, s3, -8
	s_sub_i32 s14, s8, s9
	s_cmp_gt_i32 s14, -1
	s_mov_b64 s[8:9], -1
	s_cbranch_scc0 .LBB0_261
	s_lshl_b32 s15, s14, 6
	s_mov_b64 s[8:9], 0

;     __host__ __device__ bool next(int i, Unit& u) const {
;         const long L = (long)i * G + c; if (L >= nwg) return false;
;         int wgid = (int)L; { const int q = nwg / NXCD, r = nwg % NXCD, xcd = wgid % NXCD, off = wgid / NXCD; wgid = (xcd < r ? xcd * (q + 1) : r * (q + 1) + (xcd - r) * q) + off; }
;         const int nig = WGM * nN, gid = wgid / nig, fm = gid * WGM, gsz = (nM - fm) < WGM ? (nM - fm) : WGM;
;         u.pm = fm + ((wgid % nig) % gsz); u.pn = (wgid % nig) / gsz; return true;
; template <class Epi, class Sched, bool ALIGN_EPI = false, bool SP2 = false>
; __device__ __forceinline__ void gemm_phase(PG8_LAS unsigned char* lds, const Gemm g, const Sched& S, const Epi& E) {
;     ...
;     if (!S.next(0, cur)) return;
.LBB0_1016:
	s_or_b64 exec, exec, s[0:1]
	v_mov_b32_e32 v8, v204
	s_waitcnt lgkmcnt(0)
	s_barrier
	s_and_b64 vcc, exec, s[16:17]
	v_readfirstlane_b32 s0, v8
	s_cbranch_vccnz .LBB0_1018
	s_sub_i32 s11, 0x1ff, s2
	s_lshr_b32 s1, s35, 29
	s_add_i32 s1, s11, s1
	s_and_b32 s3, s1, -8
	s_sub_i32 s3, s11, s3
	s_lshl_b32 s11, s3, 6
	s_ashr_i32 s1, s1, 3
	s_mul_i32 s10, s3, 0x41
	s_cmp_lt_i32 s3, 0
	s_cselect_b32 s3, s10, s11
	s_add_i32 s1, s3, s1
	s_ashr_i32 s3, s1, 31
	s_lshr_b32 s3, s3, 27
	s_add_i32 s3, s1, s3
	s_ashr_i32 s10, s3, 5
	s_andn2_b32 s3, s3, 31
	s_sub_i32 s1, s1, s3
	s_bfe_i32 s3, s1, 0x80000
	s_bfe_u32 s3, s3, 0x3000c
	s_add_i32 s3, s1, s3
	s_bfe_i32 s11, s3, 0x80000
	s_and_b32 s3, s3, 0xf8
	s_sub_i32 s1, s1, s3
	s_lshl_b32 s10, s10, 3
	s_sext_i32_i16 s11, s11
	s_sext_i32_i8 s1, s1
	s_add_i32 s74, s10, s1
	s_ashr_i32 s67, s11, 3

;     __host__ __device__ bool next(int i, Unit& u) const {
;         const long L = (long)i * G + c; if (L >= nwg) return false;
;         int wgid = (int)L; { const int q = nwg / NXCD, r = nwg % NXCD, xcd = wgid % NXCD, off = wgid / NXCD; wgid = (xcd < r ? xcd * (q + 1) : r * (q + 1) + (xcd - r) * q) + off; }
;         const int nig = WGM * nN, gid = wgid / nig, fm = gid * WGM, gsz = (nM - fm) < WGM ? (nM - fm) : WGM;
;         u.pm = fm + ((wgid % nig) % gsz); u.pn = (wgid % nig) / gsz; return true;
; template <class Epi, class Sched, bool ALIGN_EPI = false, bool SP2 = false>
; __device__ __forceinline__ void gemm_phase(PG8_LAS unsigned char* lds, const Gemm g, const Sched& S, const Epi& E) {
;     ...
;         const bool has_next = S.next(ui + 1, nxt);
.LBB0_1024:
	s_add_i32 s58, s58, 1
	s_mul_i32 s0, s58, s19
	s_mul_hi_u32 s1, s58, s72
	s_add_i32 s1, s1, s0
	s_mul_i32 s0, s58, s72
	s_add_u32 s12, s0, s2
	s_addc_u32 s13, s1, s35
	v_cmp_gt_i64_e32 vcc, s[12:13], v[142:143]
	v_cmp_lt_i64_e64 s[0:1], s[12:13], v[140:141]
	s_cbranch_vccnz .LBB0_1030
	s_sub_i32 s12, 0x1ff, s12
	s_ashr_i32 s13, s12, 31
	s_lshr_b32 s13, s13, 29
	s_add_i32 s48, s12, s13
	s_and_b32 s13, s48, -8
	s_sub_i32 s49, s12, s13
	s_cmp_gt_i32 s49, -1
	s_mov_b64 s[12:13], -1
	s_cbranch_scc0 .LBB0_1027
	s_lshl_b32 s54, s49, 6
	s_mov_b64 s[12:13], 0

;     __host__ __device__ bool next(int i, Unit& u) const {
;         const long L = (long)i * G + c; if (L >= nwg) return false;
;         int wgid = (int)L; { const int q = nwg / NXCD, r = nwg % NXCD, xcd = wgid % NXCD, off = wgid / NXCD; wgid = (xcd < r ? xcd * (q + 1) : r * (q + 1) + (xcd - r) * q) + off; }
;         const int nig = WGM * nN, gid = wgid / nig, fm = gid * WGM, gsz = (nM - fm) < WGM ? (nM - fm) : WGM;
;         u.pm = fm + ((wgid % nig) % gsz); u.pn = (wgid % nig) / gsz; return true;
; template <class Epi, class Sched, bool ALIGN_EPI = false, bool SP2 = false>
; __device__ __forceinline__ void gemm_phase(PG8_LAS unsigned char* lds, const Gemm g, const Sched& S, const Epi& E) {
;     ...
;     if (!S.next(0, cur)) return;
.LBB0_1178:
	s_or_b64 exec, exec, s[0:1]
	v_mov_b32_e32 v8, v204
	s_waitcnt lgkmcnt(0)
	s_barrier
	s_and_b64 vcc, exec, s[16:17]
	v_readfirstlane_b32 s0, v8
	s_cbranch_vccnz .LBB0_1180
	s_sub_i32 s12, 0x1ff, s2
	s_lshr_b32 s1, s35, 29
	s_add_i32 s1, s12, s1
	s_and_b32 s10, s1, -8
	s_sub_i32 s10, s12, s10
	s_lshl_b32 s12, s10, 6
	s_ashr_i32 s1, s1, 3
	s_mul_i32 s11, s10, 0x41
	s_cmp_lt_i32 s10, 0
	s_cselect_b32 s10, s11, s12
	s_add_i32 s1, s10, s1
	s_ashr_i32 s10, s1, 31
	s_lshr_b32 s10, s10, 27
	s_add_i32 s10, s1, s10
	s_ashr_i32 s11, s10, 5
	s_andn2_b32 s10, s10, 31
	s_sub_i32 s1, s1, s10
	s_bfe_i32 s10, s1, 0x80000
	s_bfe_u32 s10, s10, 0x3000c
	s_add_i32 s10, s1, s10
	s_bfe_i32 s12, s10, 0x80000
	s_and_b32 s10, s10, 0xf8
	s_sub_i32 s1, s1, s10
	s_lshl_b32 s11, s11, 3
	s_sext_i32_i16 s12, s12
	s_sext_i32_i8 s1, s1
	s_add_i32 s77, s11, s1
	s_ashr_i32 s76, s12, 3

;     __host__ __device__ bool next(int i, Unit& u) const {
;         const long L = (long)i * G + c; if (L >= nwg) return false;
;         int wgid = (int)L; { const int q = nwg / NXCD, r = nwg % NXCD, xcd = wgid % NXCD, off = wgid / NXCD; wgid = (xcd < r ? xcd * (q + 1) : r * (q + 1) + (xcd - r) * q) + off; }
;         const int nig = WGM * nN, gid = wgid / nig, fm = gid * WGM, gsz = (nM - fm) < WGM ? (nM - fm) : WGM;
;         u.pm = fm + ((wgid % nig) % gsz); u.pn = (wgid % nig) / gsz; return true;
; template <class Epi, class Sched, bool ALIGN_EPI = false, bool SP2 = false>
; __device__ __forceinline__ void gemm_phase(PG8_LAS unsigned char* lds, const Gemm g, const Sched& S, const Epi& E) {
;     ...
;         const bool has_next = S.next(ui + 1, nxt);
.LBB0_1186:
	s_add_i32 s61, s61, 1
	s_mul_i32 s0, s61, s19
	s_mul_hi_u32 s1, s61, s72
	s_add_i32 s1, s1, s0
	s_mul_i32 s0, s61, s72
	s_add_u32 s12, s0, s2
	s_addc_u32 s13, s1, s35
	v_cmp_gt_i64_e32 vcc, s[12:13], v[142:143]
	v_cmp_lt_i64_e64 s[0:1], s[12:13], v[140:141]
	s_cbranch_vccnz .LBB0_1192
	s_sub_i32 s12, 0x1ff, s12
	s_ashr_i32 s13, s12, 31
	s_lshr_b32 s13, s13, 29
	s_add_i32 s48, s12, s13
	s_and_b32 s13, s48, -8
	s_sub_i32 s49, s12, s13
	s_cmp_gt_i32 s49, -1
	s_mov_b64 s[12:13], -1
	s_cbranch_scc0 .LBB0_1189
	s_lshl_b32 s54, s49, 6
	s_mov_b64 s[12:13], 0

;     __host__ __device__ bool next(int i, Unit& u) const {
;         const long L = (long)i * G + c; if (L >= nwg) return false;
;         int wgid = (int)L; { const int q = nwg / NXCD, r = nwg % NXCD, xcd = wgid % NXCD, off = wgid / NXCD; wgid = (xcd < r ? xcd * (q + 1) : r * (q + 1) + (xcd - r) * q) + off; }
;         const int nig = WGM * nN, gid = wgid / nig, fm = gid * WGM, gsz = (nM - fm) < WGM ? (nM - fm) : WGM;
;         u.pm = fm + ((wgid % nig) % gsz); u.pn = (wgid % nig) / gsz; return true;
; template <class Epi, class Sched, bool ALIGN_EPI = false, bool SP2 = false>
; __device__ __forceinline__ void gemm_phase(PG8_LAS unsigned char* lds, const Gemm g, const Sched& S, const Epi& E) {
;     ...
;     if (!S.next(0, cur)) return;
.LBB0_1959:
	s_or_b64 exec, exec, s[0:1]
	v_mov_b32_e32 v8, v204
	s_waitcnt lgkmcnt(0)
	s_barrier
	s_and_b64 vcc, exec, s[16:17]
	v_readfirstlane_b32 s0, v8
	s_cbranch_vccnz .LBB0_1961
	s_sub_i32 s5, 0x1ff, s2
	s_lshr_b32 s1, s35, 29
	s_add_i32 s1, s5, s1
	s_ashr_i32 s3, s1, 3
	s_and_b32 s1, s1, -8
	s_sub_i32 s1, s5, s1
	s_lshl_b32 s5, s1, 6
	s_mul_i32 s4, s1, 0x41
	s_cmp_lt_i32 s1, 0
	s_cselect_b32 s1, s4, s5
	s_add_i32 s1, s1, s3
	s_ashr_i32 s3, s1, 31
	s_lshr_b32 s3, s3, 27
	s_add_i32 s3, s1, s3
	s_ashr_i32 s4, s3, 5
	s_and_b32 s3, s3, 0xffe0
	s_sub_i32 s1, s1, s3
	s_bfe_i32 s3, s1, 0x80000
	s_bfe_u32 s3, s3, 0x3000c
	s_add_i32 s3, s1, s3
	s_bfe_i32 s5, s3, 0x80000
	s_and_b32 s3, s3, 0xf8
	s_sub_i32 s1, s1, s3
	s_lshl_b32 s4, s4, 3
	s_sext_i32_i16 s5, s5
	s_sext_i32_i8 s1, s1
	s_add_i32 s52, s4, s1
	s_ashr_i32 s51, s5, 3

;     __host__ __device__ bool next(int i, Unit& u) const {
;         const long L = (long)i * G + c; if (L >= nwg) return false;
;         int wgid = (int)L; { const int q = nwg / NXCD, r = nwg % NXCD, xcd = wgid % NXCD, off = wgid / NXCD; wgid = (xcd < r ? xcd * (q + 1) : r * (q + 1) + (xcd - r) * q) + off; }
;         const int nig = WGM * nN, gid = wgid / nig, fm = gid * WGM, gsz = (nM - fm) < WGM ? (nM - fm) : WGM;
;         u.pm = fm + ((wgid % nig) % gsz); u.pn = (wgid % nig) / gsz; return true;
; template <class Epi, class Sched, bool ALIGN_EPI = false, bool SP2 = false>
; __device__ __forceinline__ void gemm_phase(PG8_LAS unsigned char* lds, const Gemm g, const Sched& S, const Epi& E) {
;     ...
;         const bool has_next = S.next(ui + 1, nxt);
.LBB0_1967:
	s_add_i32 s42, s42, 1
	s_mul_i32 s0, s42, s19
	s_mul_hi_u32 s1, s42, s72
	s_add_i32 s1, s1, s0
	s_mul_i32 s0, s42, s72
	s_add_u32 s4, s0, s2
	s_addc_u32 s5, s1, s35
	v_cmp_gt_i64_e32 vcc, s[4:5], v[142:143]
	v_cmp_lt_i64_e64 s[0:1], s[4:5], v[140:141]
	s_cbranch_vccnz .LBB0_1973
	s_sub_i32 s4, 0x1ff, s4
	s_ashr_i32 s5, s4, 31
	s_lshr_b32 s5, s5, 29
	s_add_i32 s24, s4, s5
	s_and_b32 s5, s24, -8
	s_sub_i32 s25, s4, s5
	s_cmp_gt_i32 s25, -1
	s_mov_b64 s[4:5], -1
	s_cbranch_scc0 .LBB0_1970
	s_lshl_b32 s36, s25, 6
	s_mov_b64 s[4:5], 0
